# v30: v29 + GLA-final output phase: LDS operand reads four pairs ahead (16 MFMAs), RMSNorm 8-lane butterflies via DPP instead of ds_bpermute
# speedup vs baseline: 1.0154x; 1.0054x over previous
; #define LAS __attribute__((address_space(3)))
; DI bf16_t f2bf(float f) { return (bf16_t)(cvt_pk(f, 0.f) & 0xffffu); }
; #define LBAR() do { asm volatile("s_waitcnt lgkmcnt(0)" ::: "memory"); __builtin_amdgcn_s_barrier(); asm volatile("" ::: "memory"); } while (0)
; DI int crow(int reg, int h) { return (reg & 3) + 8 * (reg >> 2) + 4 * h; }
; template <bool FINAL>
; DI void gla_unit(KA a, int l, int item, LAS unsigned char* lds) {
;     ...
;         {
;             const int hh = w >> 2, ww = w & 3, mi = ww >> 1, nj = ww & 1;
;             LAS bf16_t* qs = (LAS bf16_t*)(lds + hh * GL_HEAD + GL_QS); LAS bf16_t* ks = (LAS bf16_t*)(lds + hh * GL_HEAD + GL_KS); LAS bf16_t* att = (LAS bf16_t*)(lds + hh * GL_HEAD + GL_ATT);
;             f32x16 acc;
; #pragma unroll
;             for (int i = 0; i < 16; ++i) acc[i] = 0.f;
;             if (!(mi == 0 && nj == 1)) mma_blk(acc, qs + mi * 32 * 72, ks + nj * 32 * 72, r, h);
; #pragma unroll
;             for (int i = 0; i < 16; ++i) { const int irow = 32 * mi + crow(i, h), jcol = 32 * nj + r; att[irow * 72 + jcol] = f2bf(irow >= jcol ? acc[i] : 0.f); }
;         }
;         LBAR();
;         f32x16 oacc[2];
;         const int mi = w >> 2, nv = w & 3;
; #pragma unroll
;         for (int hh = 0; hh < 2; ++hh) {
;             LAS bf16_t* qs = (LAS bf16_t*)(lds + hh * GL_HEAD + GL_QS); LAS bf16_t* vT = (LAS bf16_t*)(lds + hh * GL_HEAD + GL_VT);
;             LAS bf16_t* sT = (LAS bf16_t*)(lds + hh * GL_HEAD + GL_ST); LAS bf16_t* att = (LAS bf16_t*)(lds + hh * GL_HEAD + GL_ATT);
; #pragma unroll
;             for (int i = 0; i < 16; ++i) oacc[hh][i] = 0.f;
;             mma_blk_swz(oacc[hh], att + mi * 32 * 72, vT, r, h, nv * 32);
;             mma_blk_swz(oacc[hh], qs + mi * 32 * 72, sT, r, h, nv * 32);
;         }
.LBB0_933:
	v_lshlrev_b32_e32 v74, 2, v16
	v_lshl_or_b32 v16, s4, 5, v74
	v_lshl_or_b32 v17, s5, 5, v64
	v_cmp_ge_u32_e32 vcc, v16, v17
	v_lshlrev_b32_e32 v18, 1, v17
	v_mul_u32_u24_e32 v19, 0x90, v16
	s_nop 5
	v_cndmask_b32_e32 v0, 0, v0, vcc
	v_cvt_pk_bf16_f32 v0, v0, v145
	v_add3_u32 v18, s3, v18, v19
	ds_write_b16 v18, v0 offset:59392
	v_or_b32_e32 v0, 1, v16
	v_cmp_ge_u32_e32 vcc, v0, v17
	s_mul_i32 s3, s0, 0x1200
	v_mul_u32_u24_e32 v76, 0x90, v64
	v_cndmask_b32_e32 v0, 0, v1, vcc
	v_cvt_pk_bf16_f32 v0, v0, v145
	ds_write_b16 v18, v0 offset:59536
	v_or_b32_e32 v0, 2, v16
	v_cmp_ge_u32_e32 vcc, v0, v17
	s_add_i32 s3, s3, 0
	v_add3_u32 v28, s3, v76, v65
	v_cndmask_b32_e32 v0, 0, v2, vcc
	v_cvt_pk_bf16_f32 v0, v0, v145
	ds_write_b16 v18, v0 offset:59680
	v_or_b32_e32 v0, 3, v16
	v_cmp_ge_u32_e32 vcc, v0, v17
	v_lshl_or_b32 v75, s2, 5, v64
	s_movk_i32 s4, 0x70
	v_cndmask_b32_e32 v0, 0, v3, vcc
	v_cvt_pk_bf16_f32 v0, v0, v145
	ds_write_b16 v18, v0 offset:59824
	v_or_b32_e32 v0, 8, v16
	v_cmp_ge_u32_e32 vcc, v0, v17
	s_movk_i32 s5, 0x90
	v_bitop3_b32 v77, v75, v65, s4 bitop3:0x6c
	v_cndmask_b32_e32 v0, 0, v4, vcc
	v_cvt_pk_bf16_f32 v0, v0, v145
	ds_write_b16 v18, v0 offset:60544
	v_or_b32_e32 v0, 9, v16
	v_cmp_ge_u32_e32 vcc, v0, v17
	v_mad_u32_u24 v29, v75, s5, 0
	v_add_u32_e32 v30, v29, v77
	v_cndmask_b32_e32 v0, 0, v5, vcc
	v_cvt_pk_bf16_f32 v0, v0, v145
	ds_write_b16 v18, v0 offset:60688
	v_or_b32_e32 v0, 10, v16
	v_cmp_ge_u32_e32 vcc, v0, v17
	v_or_b32_e32 v20, 32, v65
	v_bitop3_b32 v78, v75, v20, s4 bitop3:0x6c
	v_cndmask_b32_e32 v0, 0, v6, vcc
	v_cvt_pk_bf16_f32 v0, v0, v145
	ds_write_b16 v18, v0 offset:60832
	v_or_b32_e32 v0, 11, v16
	v_cmp_ge_u32_e32 vcc, v0, v17
	v_add_u32_e32 v31, v29, v78
	v_or_b32_e32 v66, 64, v65
	v_cndmask_b32_e32 v0, 0, v7, vcc
	v_cvt_pk_bf16_f32 v0, v0, v145
	ds_write_b16 v18, v0 offset:60976
	v_or_b32_e32 v0, 16, v16
	v_cmp_ge_u32_e32 vcc, v0, v17
	v_bitop3_b32 v79, v75, v66, s4 bitop3:0x6c
	v_add_u32_e32 v66, v29, v79
	v_cndmask_b32_e32 v0, 0, v8, vcc
	v_cvt_pk_bf16_f32 v0, v0, v145
	ds_write_b16 v18, v0 offset:61696
	v_or_b32_e32 v0, 17, v16
	v_cmp_ge_u32_e32 vcc, v0, v17
	v_or_b32_e32 v67, 0x60, v65
	v_bitop3_b32 v80, v75, v67, s4 bitop3:0x6c
	v_cndmask_b32_e32 v0, 0, v9, vcc
	v_cvt_pk_bf16_f32 v0, v0, v145
	ds_write_b16 v18, v0 offset:61840
	v_or_b32_e32 v0, 18, v16
	v_cmp_ge_u32_e32 vcc, v0, v17
	s_add_i32 s4, s3, 0x1f400
	v_add3_u32 v81, s4, v76, v65
	v_cndmask_b32_e32 v0, 0, v10, vcc
	v_cvt_pk_bf16_f32 v0, v0, v145
	ds_write_b16 v18, v0 offset:61984
	v_or_b32_e32 v0, 19, v16
	v_cmp_ge_u32_e32 vcc, v0, v17
	v_readlane_b32 s4, v254, 47
	s_add_i32 s3, s3, 0x11c00
	v_cndmask_b32_e32 v0, 0, v11, vcc
	v_cvt_pk_bf16_f32 v0, v0, v145
	ds_write_b16 v18, v0 offset:62128
	v_or_b32_e32 v0, 24, v16
	v_cmp_ge_u32_e32 vcc, v0, v17
	v_add3_u32 v65, s3, v76, v65
	v_readlane_b32 s3, v254, 48
	v_cndmask_b32_e32 v0, 0, v12, vcc
	v_cvt_pk_bf16_f32 v0, v0, v145
	ds_write_b16 v18, v0 offset:62848
	v_or_b32_e32 v0, 25, v16
	v_cmp_ge_u32_e32 vcc, v0, v17
	v_lshlrev_b32_e32 v64, 2, v64
	v_ashrrev_i32_e32 v85, 31, v84
	v_cndmask_b32_e32 v0, 0, v13, vcc
	v_cvt_pk_bf16_f32 v0, v0, v145
	ds_write_b16 v18, v0 offset:62992
	v_or_b32_e32 v0, 26, v16
	v_cmp_ge_u32_e32 vcc, v0, v17
	s_nop 1
	v_cndmask_b32_e32 v0, 0, v14, vcc
	v_cvt_pk_bf16_f32 v0, v0, v145
	ds_write_b16 v18, v0 offset:63136
	v_or_b32_e32 v0, 27, v16
	v_cmp_ge_u32_e32 vcc, v0, v17
	s_nop 1
	v_cndmask_b32_e32 v0, 0, v15, vcc
	v_cvt_pk_bf16_f32 v0, v0, v145
	ds_write_b16 v18, v0 offset:63280
	s_waitcnt lgkmcnt(0)
	s_barrier
	v_add_u32_e32 v120, v29, v80
	v_mov_b32_e32 v121, s4
	v_mad_u32_u24 v82, v75, s5, v121
	v_mov_b32_e32 v121, s3
	v_mad_u32_u24 v75, v75, s5, v121
	s_movk_i32 s3, 0x210
	ds_read_b128 v[88:91], v28 offset:59392
	ds_read_b128 v[92:95], v30 offset:22528
	ds_read_b128 v[96:99], v28 offset:59424
	ds_read_b128 v[100:103], v31 offset:22528
	v_add_u32_e32 v125, v82, v77
	v_add_u32_e32 v126, v82, v78
	v_add_u32_e32 v127, v82, v79
	v_add_u32_e32 v128, v82, v80
	v_add_u32_e32 v129, v75, v77
	v_add_u32_e32 v130, v75, v78
	v_add_u32_e32 v131, v75, v79
	v_add_u32_e32 v132, v75, v80
	ds_read_b128 v[104:107], v28 offset:59456
	ds_read_b128 v[108:111], v66 offset:22528
	ds_read_b128 v[112:115], v28 offset:59488
	ds_read_b128 v[116:119], v120 offset:22528
	s_waitcnt lgkmcnt(6)
	v_mfma_f32_32x32x16_bf16 v[0:15], v[88:91], v[92:95], 0
	ds_read_b128 v[88:91], v28 offset:4096
	ds_read_b128 v[92:95], v30 offset:40960
	s_waitcnt lgkmcnt(6)
	v_mfma_f32_32x32x16_bf16 v[0:15], v[96:99], v[100:103], v[0:15]
	ds_read_b128 v[96:99], v28 offset:4128
	ds_read_b128 v[100:103], v31 offset:40960
	s_waitcnt lgkmcnt(6)
	v_mfma_f32_32x32x16_bf16 v[0:15], v[104:107], v[108:111], v[0:15]
	ds_read_b128 v[104:107], v28 offset:4160
	ds_read_b128 v[108:111], v66 offset:40960
	s_waitcnt lgkmcnt(6)
	v_mfma_f32_32x32x16_bf16 v[0:15], v[112:115], v[116:119], v[0:15]
	ds_read_b128 v[112:115], v28 offset:4192
	ds_read_b128 v[116:119], v120 offset:40960
	s_waitcnt lgkmcnt(6)
	v_mfma_f32_32x32x16_bf16 v[0:15], v[88:91], v[92:95], v[0:15]
	ds_read_b128 v[88:91], v81
	ds_read_b128 v[92:95], v125
	s_waitcnt lgkmcnt(6)
	v_mfma_f32_32x32x16_bf16 v[0:15], v[96:99], v[100:103], v[0:15]
	ds_read_b128 v[96:99], v81 offset:32
	ds_read_b128 v[100:103], v126
	s_waitcnt lgkmcnt(6)
	v_mfma_f32_32x32x16_bf16 v[0:15], v[104:107], v[108:111], v[0:15]
	ds_read_b128 v[104:107], v81 offset:64
	ds_read_b128 v[108:111], v127
	s_waitcnt lgkmcnt(6)
	v_mfma_f32_32x32x16_bf16 v[0:15], v[112:115], v[116:119], v[0:15]
	ds_read_b128 v[112:115], v81 offset:96
	ds_read_b128 v[116:119], v128
	s_waitcnt lgkmcnt(6)
	v_mfma_f32_32x32x16_bf16 v[16:31], v[88:91], v[92:95], 0
	ds_read_b128 v[88:91], v65
	ds_read_b128 v[92:95], v129
	s_waitcnt lgkmcnt(6)
	v_mfma_f32_32x32x16_bf16 v[16:31], v[96:99], v[100:103], v[16:31]
	ds_read_b128 v[96:99], v65 offset:32
	ds_read_b128 v[100:103], v130
	s_waitcnt lgkmcnt(6)
	v_mfma_f32_32x32x16_bf16 v[16:31], v[104:107], v[108:111], v[16:31]
	ds_read_b128 v[104:107], v65 offset:64
	ds_read_b128 v[108:111], v131
	s_waitcnt lgkmcnt(6)
	v_mfma_f32_32x32x16_bf16 v[16:31], v[112:115], v[116:119], v[16:31]
	ds_read_b128 v[112:115], v65 offset:96
	ds_read_b128 v[116:119], v132
	s_waitcnt lgkmcnt(6)
	v_mfma_f32_32x32x16_bf16 v[16:31], v[88:91], v[92:95], v[16:31]
	s_waitcnt lgkmcnt(4)
	v_mfma_f32_32x32x16_bf16 v[16:31], v[96:99], v[100:103], v[16:31]
	s_waitcnt lgkmcnt(2)
	v_mfma_f32_32x32x16_bf16 v[16:31], v[104:107], v[108:111], v[16:31]
	v_lshl_or_b32 v65, s0, 5, v74
	s_lshl_b32 s0, s2, 7
	s_add_i32 s2, s0, 0
	v_mul_lo_u32 v65, v65, s3
	s_waitcnt lgkmcnt(0)
	v_mfma_f32_32x32x16_bf16 v[16:31], v[112:115], v[116:119], v[16:31]
	v_add3_u32 v66, s2, v64, v65
	v_add_u32_e32 v67, 0x5800, v66
	s_waitcnt lgkmcnt(0)
	s_barrier
; #define LAS __attribute__((address_space(3)))
; #define LBAR() do { asm volatile("s_waitcnt lgkmcnt(0)" ::: "memory"); __builtin_amdgcn_s_barrier(); asm volatile("" ::: "memory"); } while (0)
; DI int crow(int reg, int h) { return (reg & 3) + 8 * (reg >> 2) + 4 * h; }
; template <bool FINAL>
; DI void gla_unit(KA a, int l, int item, LAS unsigned char* lds) {
;     ...
;         for (int hh = 0; hh < 2; ++hh) {
;             LAS float* ob = (LAS float*)(lds + hh * GL_HEAD + GL_VT);
; #pragma unroll
;             for (int i = 0; i < 16; ++i) ob[(32 * mi + crow(i, h)) * 132 + 32 * nv + r] = oacc[hh][i];
;         }
;         LBAR();
; #pragma unroll
;         for (int hh = 0; hh < 2; ++hh) {
;             const int hd = 2 * hp + hh;
;             const LAS float* ob = (const LAS float*)(lds + hh * GL_HEAD + GL_VT);
;             const int i = vj, dvc = vdvc;
;             float o[16];
; #pragma unroll
;             for (int q = 0; q < 4; ++q) { const f32x4 v = *(const LAS f32x4*)(ob + i * 132 + dvc + 4 * q); o[4 * q] = v.x; o[4 * q + 1] = v.y; o[4 * q + 2] = v.z; o[4 * q + 3] = v.w; }
;             float s = 0.f;
; #pragma unroll
;             for (int e = 0; e < 16; ++e) s += o[e] * o[e];
;             s += __shfl_xor(s, 1); s += __shfl_xor(s, 2); s += __shfl_xor(s, 4);
;             const float rs = rsqrtf(s * (1.f / DV) + EPS);
	ds_write2_b32 v67, v0, v1 offset1:132
	v_add_u32_e32 v0, 0x5c00, v66
	ds_write2_b32 v0, v2, v3 offset0:8 offset1:140
	v_add_u32_e32 v0, 0x6800, v66
	ds_write2_b32 v0, v4, v5 offset0:32 offset1:164
	v_add_u32_e32 v0, 0x6c00, v66
	ds_write2_b32 v0, v6, v7 offset0:40 offset1:172
	v_add_u32_e32 v0, 0x7800, v66
	ds_write2_b32 v0, v8, v9 offset0:64 offset1:196
	v_add_u32_e32 v0, 0x7c00, v66
	ds_write2_b32 v0, v10, v11 offset0:72 offset1:204
	v_add_u32_e32 v0, 0x8800, v66
	ds_write2_b32 v0, v12, v13 offset0:96 offset1:228
	v_add_u32_e32 v0, 0x8c00, v66
	s_add_i32 s0, s4, s0
	ds_write2_b32 v0, v14, v15 offset0:104 offset1:236
	v_add3_u32 v0, s0, v64, v65
	v_add_u32_e32 v1, 0x400, v0
	ds_write2_b32 v1, v18, v19 offset0:8 offset1:140
	v_add_u32_e32 v1, 0x1000, v0
	ds_write2_b32 v1, v20, v21 offset0:32 offset1:164
	v_add_u32_e32 v1, 0x1400, v0
	ds_write2_b32 v1, v22, v23 offset0:40 offset1:172
	v_add_u32_e32 v1, 0x2000, v0
	ds_write2_b32 v1, v24, v25 offset0:64 offset1:196
	v_add_u32_e32 v1, 0x2400, v0
	ds_write2_b32 v0, v16, v17 offset1:132
	ds_write2_b32 v1, v26, v27 offset0:72 offset1:204
	v_add_u32_e32 v1, 0x3000, v0
	v_add_u32_e32 v0, 0x3400, v0
	ds_write2_b32 v1, v28, v29 offset0:96 offset1:228
	ds_write2_b32 v0, v30, v31 offset0:104 offset1:236
	v_mul_lo_u32 v66, v122, s3
	v_and_b32_e32 v1, 64, v221
	s_waitcnt lgkmcnt(0)
	s_barrier
	v_add_u32_e32 v16, 64, v1
	v_add3_u32 v1, 0, v66, v124
	ds_read_b128 v[12:15], v1 offset:22528
	v_xor_b32_e32 v0, 1, v221
	v_cmp_lt_i32_e32 vcc, v0, v16
	v_xor_b32_e32 v19, 2, v221
	s_mov_b64 s[2:3], 0xaf00400
	v_cndmask_b32_e32 v0, v221, v0, vcc
	s_waitcnt lgkmcnt(0)
	v_mul_f32_e32 v17, v13, v13
	v_lshlrev_b32_e32 v67, 2, v0
	ds_read_b128 v[8:11], v1 offset:22544
	ds_read_b128 v[4:7], v1 offset:22560
	ds_read_b128 v[0:3], v1 offset:22576
	v_fmac_f32_e32 v17, v12, v12
	v_fmac_f32_e32 v17, v14, v14
	v_fmac_f32_e32 v17, v15, v15
	s_waitcnt lgkmcnt(2)
	v_fmac_f32_e32 v17, v8, v8
	v_fmac_f32_e32 v17, v9, v9
	v_fmac_f32_e32 v17, v10, v10
	v_fmac_f32_e32 v17, v11, v11
	s_waitcnt lgkmcnt(1)
	v_fmac_f32_e32 v17, v4, v4
	v_fmac_f32_e32 v17, v5, v5
	v_fmac_f32_e32 v17, v6, v6
	v_fmac_f32_e32 v17, v7, v7
	s_waitcnt lgkmcnt(0)
	v_fmac_f32_e32 v17, v0, v0
	v_fmac_f32_e32 v17, v1, v1
	v_fmac_f32_e32 v17, v2, v2
	v_fmac_f32_e32 v17, v3, v3
	s_nop 1
	v_add_f32_dpp v17, v17, v17 quad_perm:[1,0,3,2] row_mask:0xf bank_mask:0xf
	v_cmp_lt_i32_e32 vcc, v19, v16
	v_cndmask_b32_e32 v19, v221, v19, vcc
	v_lshlrev_b32_e32 v68, 2, v19
	s_nop 1
	v_add_f32_dpp v18, v17, v17 quad_perm:[2,3,0,1] row_mask:0xf bank_mask:0xf
	v_xor_b32_e32 v19, 4, v221
	v_cmp_lt_i32_e32 vcc, v19, v16
	v_cndmask_b32_e32 v16, v221, v19, vcc
	v_lshlrev_b32_e32 v69, 2, v16
	s_nop 1
	v_add_f32_dpp v19, v18, v18 row_half_mirror row_mask:0xf bank_mask:0xf
	v_lshlrev_b64 v[16:17], 11, v[84:85]
	v_lshl_add_u64 v[16:17], s[28:29], 0, v[16:17]
	v_lshl_add_u64 v[16:17], v[16:17], 0, v[144:145]
	v_lshl_add_u64 v[16:17], v[16:17], 0, s[2:3]
	s_and_saveexec_b64 s[2:3], s[8:9]
	s_cbranch_execz .LBB0_935
	s_waitcnt lgkmcnt(0)
	v_mov_b32_e32 v18, v19
	v_fmamk_f32 v18, v18, 0x3c000000, v217
	s_mov_b32 s0, 0x800000
	v_cmp_gt_f32_e32 vcc, s0, v18
	v_mul_f32_e32 v19, 0x4b800000, v18
	v_lshlrev_b32_e32 v70, 16, v40
	v_cndmask_b32_e32 v18, v18, v19, vcc
	v_rsq_f32_e32 v18, v18
	v_and_b32_e32 v72, 0xffff0000, v40
	v_lshlrev_b32_e32 v40, 16, v36
	v_and_b32_e32 v30, 0xffff0000, v36
	v_mul_f32_e32 v19, 0x45800000, v18
	v_cndmask_b32_e32 v19, v18, v19, vcc
	v_mul_f32_e32 v71, v12, v19
	v_mul_f32_e32 v12, 0xbfb8aa3b, v70
	v_exp_f32_e32 v12, v12
	v_mul_f32_e32 v73, v13, v19
	v_mul_f32_e32 v13, 0xbfb8aa3b, v72
	v_exp_f32_e32 v13, v13
	v_add_f32_e32 v12, 1.0, v12
	v_rcp_f32_e32 v36, v12
	v_lshlrev_b32_e32 v74, 16, v41
	v_lshlrev_b32_e32 v28, 16, v37
	v_and_b32_e32 v26, 0xffff0000, v37
	v_mov_b32_e32 v37, v60
	v_pk_mul_f32 v[36:37], v[36:37], v[70:71]
	v_add_f32_e32 v13, 1.0, v13
	v_mul_f32_e32 v75, v14, v19
	v_mul_f32_e32 v14, 0xbfb8aa3b, v74
	v_mul_f32_e32 v12, v36, v37
	v_rcp_f32_e32 v36, v13
	v_exp_f32_e32 v14, v14
	v_mov_b32_e32 v37, v61
	v_and_b32_e32 v76, 0xffff0000, v41
	v_pk_mul_f32 v[36:37], v[36:37], v[72:73]
	v_add_f32_e32 v14, 1.0, v14
	v_mul_f32_e32 v13, v36, v37
	v_rcp_f32_e32 v36, v14
	v_mul_f32_e32 v14, 0xbfb8aa3b, v76
	v_exp_f32_e32 v14, v14
	v_lshlrev_b32_e32 v78, 16, v42
	v_mul_f32_e32 v79, v8, v19
	v_mul_f32_e32 v8, 0xbfb8aa3b, v78
	v_add_f32_e32 v14, 1.0, v14
	v_rcp_f32_e32 v14, v14
	v_exp_f32_e32 v8, v8
	v_mov_b32_e32 v37, v62
	v_mul_f32_e32 v77, v15, v19
	v_mov_b32_e32 v15, v63
	v_and_b32_e32 v80, 0xffff0000, v42
	v_pk_mul_f32 v[36:37], v[36:37], v[74:75]
	v_pk_mul_f32 v[14:15], v[14:15], v[76:77]
	v_add_f32_e32 v8, 1.0, v8
	v_mul_f32_e32 v36, v36, v37
	v_mul_f32_e32 v37, v14, v15
	v_rcp_f32_e32 v14, v8
	v_mul_f32_e32 v8, 0xbfb8aa3b, v80
	v_exp_f32_e32 v8, v8
	v_mov_b32_e32 v15, v56
	v_mul_f32_e32 v81, v9, v19
	v_mov_b32_e32 v9, v57
	v_add_f32_e32 v8, 1.0, v8
	v_rcp_f32_e32 v8, v8
	v_lshlrev_b32_e32 v64, 16, v43
	v_pk_mul_f32 v[14:15], v[14:15], v[78:79]
	v_mul_f32_e32 v65, v10, v19
	v_pk_mul_f32 v[8:9], v[8:9], v[80:81]
	v_mul_f32_e32 v14, v14, v15
	v_mul_f32_e32 v15, v8, v9
	v_mul_f32_e32 v8, 0xbfb8aa3b, v64
	v_exp_f32_e32 v8, v8
	v_mov_b32_e32 v9, v58
	v_and_b32_e32 v42, 0xffff0000, v43
	v_mul_f32_e32 v41, v4, v19
	v_add_f32_e32 v8, 1.0, v8
	v_rcp_f32_e32 v8, v8
	v_mul_f32_e32 v4, 0xbfb8aa3b, v40
	v_exp_f32_e32 v4, v4
	v_mul_f32_e32 v43, v11, v19
	v_pk_mul_f32 v[8:9], v[8:9], v[64:65]
	v_mul_f32_e32 v31, v5, v19
	v_mul_f32_e32 v10, v8, v9
	v_mul_f32_e32 v8, 0xbfb8aa3b, v42
	v_exp_f32_e32 v8, v8
	v_mov_b32_e32 v9, v59
	v_add_f32_e32 v4, 1.0, v4
	v_mov_b32_e32 v5, v53
; DI unsigned cvt_pk(float lo, float hi) { unsigned r; asm("v_cvt_pk_bf16_f32 %0, %1, %2" : "=v"(r) : "v"(lo), "v"(hi)); return r; }
; DI float siluf_(float x) { return x * sigmoidf_(x); }
; template <bool FINAL>
; DI void gla_unit(KA a, int l, int item, LAS unsigned char* lds) {
;     ...
;                 float go[16]; unpack8(g0[hh], go); unpack8(g1[hh], go + 8);
;                 float y[16];
; #pragma unroll
;                 for (int e = 0; e < 16; ++e) y[e] = o[e] * rs * gnv[e >> 2][e & 3] * siluf_(go[e]);
;                 u32x4 w0, w1;
;                 w0.x = cvt_pk(y[0], y[1]); w0.y = cvt_pk(y[2], y[3]); w0.z = cvt_pk(y[4], y[5]); w0.w = cvt_pk(y[6], y[7]);
;                 w1.x = cvt_pk(y[8], y[9]); w1.y = cvt_pk(y[10], y[11]); w1.z = cvt_pk(y[12], y[13]); w1.w = cvt_pk(y[14], y[15]);
;                 u32x4* yp = (u32x4*)((bf16_t*)(a->ws + WS_Y) + (size_t)(row0 + i) * DM + DLRU + hd * 128 + dvc);
;                 yp[0] = w0; yp[1] = w1;
	v_add_f32_e32 v8, 1.0, v8
	v_rcp_f32_e32 v8, v8
	v_mul_f32_e32 v29, v6, v19
	v_lshlrev_b32_e32 v24, 16, v38
	v_mul_f32_e32 v25, v0, v19
	v_pk_mul_f32 v[8:9], v[8:9], v[42:43]
	v_mul_f32_e32 v0, 0xbfb8aa3b, v24
	v_mul_f32_e32 v11, v8, v9
	v_rcp_f32_e32 v8, v4
	v_mul_f32_e32 v4, 0xbfb8aa3b, v30
	v_exp_f32_e32 v4, v4
	v_mov_b32_e32 v9, v52
	v_pk_mul_f32 v[8:9], v[8:9], v[40:41]
	v_exp_f32_e32 v0, v0
	v_add_f32_e32 v4, 1.0, v4
	v_rcp_f32_e32 v4, v4
	v_mul_f32_e32 v8, v8, v9
	v_mul_f32_e32 v27, v7, v19
	v_and_b32_e32 v22, 0xffff0000, v38
	v_pk_mul_f32 v[4:5], v[4:5], v[30:31]
	v_add_f32_e32 v0, 1.0, v0
	v_mul_f32_e32 v9, v4, v5
	v_mul_f32_e32 v4, 0xbfb8aa3b, v28
	v_exp_f32_e32 v4, v4
	v_mov_b32_e32 v5, v54
	v_mul_f32_e32 v23, v1, v19
	v_mov_b32_e32 v1, v33
	v_add_f32_e32 v4, 1.0, v4
	v_rcp_f32_e32 v4, v4
	v_lshlrev_b32_e32 v20, 16, v39
	v_mul_f32_e32 v21, v2, v19
	v_and_b32_e32 v18, 0xffff0000, v39
	v_pk_mul_f32 v[4:5], v[4:5], v[28:29]
	v_mul_f32_e32 v19, v3, v19
	v_mul_f32_e32 v6, v4, v5
	v_mul_f32_e32 v4, 0xbfb8aa3b, v26
	v_exp_f32_e32 v4, v4
	v_mov_b32_e32 v5, v55
	s_lshl_b32 s0, s42, 1
	v_cvt_pk_bf16_f32 v2, v14, v15
	v_add_f32_e32 v4, 1.0, v4
	v_rcp_f32_e32 v4, v4
	v_cvt_pk_bf16_f32 v3, v10, v11
	s_nop 0
	v_pk_mul_f32 v[4:5], v[4:5], v[26:27]
	s_nop 0
	v_mul_f32_e32 v7, v4, v5
	v_rcp_f32_e32 v4, v0
	v_mul_f32_e32 v0, 0xbfb8aa3b, v22
	v_exp_f32_e32 v0, v0
	v_mov_b32_e32 v5, v32
	v_pk_mul_f32 v[4:5], v[4:5], v[24:25]
	v_add_f32_e32 v0, 1.0, v0
	v_rcp_f32_e32 v0, v0
	v_mul_f32_e32 v24, v4, v5
	v_cvt_pk_bf16_f32 v4, v8, v9
	v_lshl_add_u64 v[8:9], v[16:17], 0, s[0:1]
	v_pk_mul_f32 v[0:1], v[0:1], v[22:23]
	v_cvt_pk_bf16_f32 v5, v6, v7
	s_nop 0
	v_mul_f32_e32 v22, v0, v1
	v_mul_f32_e32 v0, 0xbfb8aa3b, v20
	v_exp_f32_e32 v0, v0
	v_mov_b32_e32 v1, v34
	v_cvt_pk_bf16_f32 v6, v24, v22
	v_add_f32_e32 v0, 1.0, v0
	v_rcp_f32_e32 v0, v0
	s_nop 0
	v_pk_mul_f32 v[0:1], v[0:1], v[20:21]
	s_nop 0
	v_mul_f32_e32 v20, v0, v1
	v_mul_f32_e32 v0, 0xbfb8aa3b, v18
	v_exp_f32_e32 v0, v0
	v_mov_b32_e32 v1, v35
	v_add_f32_e32 v0, 1.0, v0
	v_rcp_f32_e32 v0, v0
	s_nop 0
	v_pk_mul_f32 v[0:1], v[0:1], v[18:19]
	s_nop 0
	v_mul_f32_e32 v18, v0, v1
	v_cvt_pk_bf16_f32 v0, v12, v13
	v_cvt_pk_bf16_f32 v1, v36, v37
	v_cvt_pk_bf16_f32 v7, v20, v18
	global_store_dwordx4 v[8:9], v[0:3], off
	global_store_dwordx4 v[8:9], v[4:7], off offset:16
; #define LAS __attribute__((address_space(3)))
; DI unsigned cvt_pk(float lo, float hi) { unsigned r; asm("v_cvt_pk_bf16_f32 %0, %1, %2" : "=v"(r) : "v"(lo), "v"(hi)); return r; }
; DI float siluf_(float x) { return x * sigmoidf_(x); }
; template <bool FINAL>
; DI void gla_unit(KA a, int l, int item, LAS unsigned char* lds) {
;     ...
;         for (int hh = 0; hh < 2; ++hh) {
;             const int hd = 2 * hp + hh;
;             const LAS float* ob = (const LAS float*)(lds + hh * GL_HEAD + GL_VT);
;             const int i = vj, dvc = vdvc;
;             float o[16];
; #pragma unroll
;             for (int q = 0; q < 4; ++q) { const f32x4 v = *(const LAS f32x4*)(ob + i * 132 + dvc + 4 * q); o[4 * q] = v.x; o[4 * q + 1] = v.y; o[4 * q + 2] = v.z; o[4 * q + 3] = v.w; }
;             float s = 0.f;
; #pragma unroll
;             for (int e = 0; e < 16; ++e) s += o[e] * o[e];
;             s += __shfl_xor(s, 1); s += __shfl_xor(s, 2); s += __shfl_xor(s, 4);
;             const float rs = rsqrtf(s * (1.f / DV) + EPS);
;             if (i < nvalid) {
;                 float go[16]; unpack8(g0[hh], go); unpack8(g1[hh], go + 8);
;                 float y[16];
; #pragma unroll
;                 for (int e = 0; e < 16; ++e) y[e] = o[e] * rs * gnv[e >> 2][e & 3] * siluf_(go[e]);
;                 u32x4 w0, w1;
;                 w0.x = cvt_pk(y[0], y[1]); w0.y = cvt_pk(y[2], y[3]); w0.z = cvt_pk(y[4], y[5]); w0.w = cvt_pk(y[6], y[7]);
;                 w1.x = cvt_pk(y[8], y[9]); w1.y = cvt_pk(y[10], y[11]); w1.z = cvt_pk(y[12], y[13]); w1.w = cvt_pk(y[14], y[15]);
;                 u32x4* yp = (u32x4*)((bf16_t*)(a->ws + WS_Y) + (size_t)(row0 + i) * DM + DLRU + hd * 128 + dvc);
;                 yp[0] = w0; yp[1] = w1;
.LBB0_935:
	s_or_b64 exec, exec, s[2:3]
	v_readlane_b32 s0, v254, 47
	s_nop 1
	v_add3_u32 v0, s0, v66, v124
	ds_read_b128 v[12:15], v0
	ds_read_b128 v[8:11], v0 offset:16
	ds_read_b128 v[4:7], v0 offset:32
	ds_read_b128 v[0:3], v0 offset:48
	s_waitcnt lgkmcnt(3)
	v_mul_f32_e32 v18, v13, v13
	v_fmac_f32_e32 v18, v12, v12
	v_fmac_f32_e32 v18, v14, v14
	v_fmac_f32_e32 v18, v15, v15
	s_waitcnt lgkmcnt(2)
	v_fmac_f32_e32 v18, v8, v8
	v_fmac_f32_e32 v18, v9, v9
	v_fmac_f32_e32 v18, v10, v10
	v_fmac_f32_e32 v18, v11, v11
	s_waitcnt lgkmcnt(1)
	v_fmac_f32_e32 v18, v4, v4
	v_fmac_f32_e32 v18, v5, v5
	v_fmac_f32_e32 v18, v6, v6
	v_fmac_f32_e32 v18, v7, v7
	s_waitcnt lgkmcnt(0)
	v_fmac_f32_e32 v18, v0, v0
	v_fmac_f32_e32 v18, v1, v1
	v_fmac_f32_e32 v18, v2, v2
	v_fmac_f32_e32 v18, v3, v3
	s_nop 1
	v_add_f32_dpp v18, v18, v18 quad_perm:[1,0,3,2] row_mask:0xf bank_mask:0xf
	s_nop 1
	v_add_f32_dpp v18, v18, v18 quad_perm:[2,3,0,1] row_mask:0xf bank_mask:0xf
	s_nop 1
	v_add_f32_dpp v18, v18, v18 row_half_mirror row_mask:0xf bank_mask:0xf
	s_and_saveexec_b64 s[2:3], s[8:9]
	s_cbranch_execz .LBB0_937
	s_waitcnt lgkmcnt(0)
	v_fmamk_f32 v18, v18, 0x3c000000, v217
	s_mov_b32 s0, 0x800000
	v_cmp_gt_f32_e32 vcc, s0, v18
	v_mul_f32_e32 v19, 0x4b800000, v18
	v_lshlrev_b32_e32 v42, 16, v48
	v_cndmask_b32_e32 v18, v18, v19, vcc
	v_rsq_f32_e32 v18, v18
	v_and_b32_e32 v48, 0xffff0000, v48
	v_lshlrev_b32_e32 v64, 16, v49
	v_and_b32_e32 v66, 0xffff0000, v49
	v_mul_f32_e32 v19, 0x45800000, v18
	v_cndmask_b32_e32 v19, v18, v19, vcc
	v_mul_f32_e32 v43, v12, v19
	v_mul_f32_e32 v12, 0xbfb8aa3b, v42
	v_exp_f32_e32 v12, v12
	v_mul_f32_e32 v49, v13, v19
	v_mul_f32_e32 v13, 0xbfb8aa3b, v48
	v_exp_f32_e32 v13, v13
	v_add_f32_e32 v12, 1.0, v12
	v_lshlrev_b32_e32 v36, 16, v44
	v_and_b32_e32 v30, 0xffff0000, v44
	v_rcp_f32_e32 v44, v12
	v_add_f32_e32 v13, 1.0, v13
	v_mul_f32_e32 v65, v14, v19
	v_mul_f32_e32 v14, 0xbfb8aa3b, v64
	v_lshlrev_b32_e32 v28, 16, v45
	v_and_b32_e32 v26, 0xffff0000, v45
	v_mov_b32_e32 v45, v60
	v_rcp_f32_e32 v60, v13
	v_exp_f32_e32 v14, v14
	v_mul_f32_e32 v67, v15, v19
	v_mul_f32_e32 v15, 0xbfb8aa3b, v66
	v_exp_f32_e32 v15, v15
	v_pk_mul_f32 v[42:43], v[44:45], v[42:43]
	v_lshlrev_b32_e32 v68, 16, v50
	v_mul_f32_e32 v12, v42, v43
	v_pk_mul_f32 v[42:43], v[60:61], v[48:49]
	v_add_f32_e32 v14, 1.0, v14
	v_mul_f32_e32 v13, v42, v43
	v_rcp_f32_e32 v42, v14
	v_add_f32_e32 v15, 1.0, v15
	v_mul_f32_e32 v69, v8, v19
	v_mul_f32_e32 v8, 0xbfb8aa3b, v68
	v_mov_b32_e32 v43, v62
	v_rcp_f32_e32 v62, v15
	v_exp_f32_e32 v8, v8
	v_pk_mul_f32 v[42:43], v[42:43], v[64:65]
	v_and_b32_e32 v50, 0xffff0000, v50
	v_mul_f32_e32 v14, v42, v43
	v_pk_mul_f32 v[42:43], v[62:63], v[66:67]
	v_add_f32_e32 v8, 1.0, v8
	v_mul_f32_e32 v15, v42, v43
	v_rcp_f32_e32 v42, v8
	v_mul_f32_e32 v8, 0xbfb8aa3b, v50
	v_exp_f32_e32 v8, v8
	v_mov_b32_e32 v43, v56
	v_lshlrev_b32_e32 v40, 16, v51
	v_and_b32_e32 v38, 0xffff0000, v51
	v_add_f32_e32 v8, 1.0, v8
	v_rcp_f32_e32 v56, v8
	v_mul_f32_e32 v51, v9, v19
	v_pk_mul_f32 v[42:43], v[42:43], v[68:69]
	v_mul_f32_e32 v41, v10, v19
	v_pk_mul_f32 v[8:9], v[56:57], v[50:51]
	v_mul_f32_e32 v42, v42, v43
	v_mul_f32_e32 v43, v8, v9
	v_mul_f32_e32 v8, 0xbfb8aa3b, v40
	v_exp_f32_e32 v8, v8
	v_mov_b32_e32 v9, v58
	v_mul_f32_e32 v37, v4, v19
	v_mul_f32_e32 v4, 0xbfb8aa3b, v36
	v_add_f32_e32 v8, 1.0, v8
	v_rcp_f32_e32 v8, v8
	v_exp_f32_e32 v4, v4
	v_mul_f32_e32 v39, v11, v19
	v_mul_f32_e32 v31, v5, v19
	v_pk_mul_f32 v[8:9], v[8:9], v[40:41]
	v_add_f32_e32 v4, 1.0, v4
	v_mul_f32_e32 v10, v8, v9
	v_mul_f32_e32 v8, 0xbfb8aa3b, v38
	v_exp_f32_e32 v8, v8
	v_mul_f32_e32 v29, v6, v19
	v_lshlrev_b32_e32 v24, 16, v46
	v_mul_f32_e32 v25, v0, v19
	v_add_f32_e32 v8, 1.0, v8
	v_rcp_f32_e32 v58, v8
	v_mul_f32_e32 v0, 0xbfb8aa3b, v24
	v_exp_f32_e32 v0, v0
	v_mul_f32_e32 v27, v7, v19
	v_pk_mul_f32 v[8:9], v[58:59], v[38:39]
	v_and_b32_e32 v22, 0xffff0000, v46
	v_mul_f32_e32 v11, v8, v9
	v_rcp_f32_e32 v8, v4
	v_mul_f32_e32 v4, 0xbfb8aa3b, v30
	v_exp_f32_e32 v4, v4
	v_mov_b32_e32 v9, v52
	v_pk_mul_f32 v[8:9], v[8:9], v[36:37]
	v_add_f32_e32 v0, 1.0, v0
	v_add_f32_e32 v4, 1.0, v4
	v_rcp_f32_e32 v52, v4
	v_mul_f32_e32 v8, v8, v9
	v_mul_f32_e32 v23, v1, v19
	v_lshlrev_b32_e32 v20, 16, v47
	v_pk_mul_f32 v[4:5], v[52:53], v[30:31]
	v_mul_f32_e32 v21, v2, v19
	v_mul_f32_e32 v9, v4, v5
	v_mul_f32_e32 v4, 0xbfb8aa3b, v28
	v_exp_f32_e32 v4, v4
	v_mov_b32_e32 v5, v54
	v_and_b32_e32 v18, 0xffff0000, v47
	v_mul_f32_e32 v19, v3, v19
	v_add_f32_e32 v4, 1.0, v4
	v_rcp_f32_e32 v4, v4
	s_lshl_b32 s0, s42, 1
	v_cvt_pk_bf16_f32 v2, v42, v43
	v_cvt_pk_bf16_f32 v3, v10, v11
	v_pk_mul_f32 v[4:5], v[4:5], v[28:29]
	s_nop 0
	v_mul_f32_e32 v6, v4, v5
	v_mul_f32_e32 v4, 0xbfb8aa3b, v26
	v_exp_f32_e32 v4, v4
	s_nop 0
	v_add_f32_e32 v4, 1.0, v4
	v_rcp_f32_e32 v54, v4
	s_nop 0
	v_pk_mul_f32 v[4:5], v[54:55], v[26:27]
	s_nop 0
	v_mul_f32_e32 v7, v4, v5
	v_rcp_f32_e32 v4, v0
	v_mul_f32_e32 v0, 0xbfb8aa3b, v22
	v_exp_f32_e32 v0, v0
	v_mov_b32_e32 v5, v32
	v_pk_mul_f32 v[4:5], v[4:5], v[24:25]
	v_add_f32_e32 v0, 1.0, v0
	v_rcp_f32_e32 v32, v0
	v_mul_f32_e32 v24, v4, v5
	v_cvt_pk_bf16_f32 v4, v8, v9
	v_lshl_add_u64 v[8:9], v[16:17], 0, s[0:1]
	v_pk_mul_f32 v[0:1], v[32:33], v[22:23]
	v_cvt_pk_bf16_f32 v5, v6, v7
	s_nop 0
	v_mul_f32_e32 v22, v0, v1
	v_mul_f32_e32 v0, 0xbfb8aa3b, v20
	v_exp_f32_e32 v0, v0
	v_mov_b32_e32 v1, v34
	v_cvt_pk_bf16_f32 v6, v24, v22
	v_add_f32_e32 v0, 1.0, v0
	v_rcp_f32_e32 v0, v0
	s_nop 0
	v_pk_mul_f32 v[0:1], v[0:1], v[20:21]
	s_nop 0
	v_mul_f32_e32 v20, v0, v1
	v_mul_f32_e32 v0, 0xbfb8aa3b, v18
	v_exp_f32_e32 v0, v0
	s_nop 0
	v_add_f32_e32 v0, 1.0, v0
	v_rcp_f32_e32 v34, v0
	s_nop 0
	v_pk_mul_f32 v[0:1], v[34:35], v[18:19]
	s_nop 0
	v_mul_f32_e32 v18, v0, v1
	v_cvt_pk_bf16_f32 v0, v12, v13
	v_cvt_pk_bf16_f32 v1, v14, v15
	v_cvt_pk_bf16_f32 v7, v20, v18
	global_store_dwordx4 v[8:9], v[0:3], off offset:256
	global_store_dwordx4 v[8:9], v[4:7], off offset:272
